# mixers softmax: DPP butterfly stages fused into v_max_f32_dpp / v_add_f32_dpp (drops mov+canonicalize per stage)
# baseline (speedup 1.0000x reference)
.LBB0_870:
	s_nop 6
	v_max_f32_e32 v56, v40, v40
	v_max_f32_e32 v57, v36, v36
	v_max_f32_e32 v56, v57, v56
	v_max3_f32 v56, v28, v32, v56
	s_nop 1
	v_max_f32_dpp v56, v56, v56 row_ror:8 row_mask:0xf bank_mask:0xf
	s_nop 1
	v_max_f32_dpp v56, v56, v56 row_ror:4 row_mask:0xf bank_mask:0xf
	s_nop 1
	v_max_f32_dpp v56, v56, v56 row_ror:2 row_mask:0xf bank_mask:0xf
	v_mov_b32_e32 v57, v0
	s_nop 1
	v_mov_b32_dpp v57, v56 row_ror:1 row_mask:0xf bank_mask:0xf
	v_max3_f32 v82, v80, v56, v57
	v_sub_f32_e32 v28, v28, v82
	v_mul_f32_e32 v28, 0x3fb8aa3b, v28
	v_exp_f32_e32 v63, v28
	v_sub_f32_e32 v28, v32, v82
	v_mul_f32_e32 v28, 0x3fb8aa3b, v28
	v_exp_f32_e32 v61, v28
	v_sub_f32_e32 v28, v36, v82
	v_mul_f32_e32 v28, 0x3fb8aa3b, v28
	v_exp_f32_e32 v59, v28
	v_sub_f32_e32 v28, v40, v82
	v_mul_f32_e32 v28, 0x3fb8aa3b, v28
	v_exp_f32_e32 v57, v28
	v_max_f32_e32 v28, v41, v41
	v_max_f32_e32 v32, v37, v37
	v_max_f32_e32 v28, v32, v28
	v_max3_f32 v28, v29, v33, v28
	v_sub_f32_e32 v56, v80, v82
	v_mul_f32_e32 v56, 0x3fb8aa3b, v56
	v_max_f32_dpp v28, v28, v28 row_ror:8 row_mask:0xf bank_mask:0xf
	v_exp_f32_e32 v81, v56
	s_nop 0
	v_max_f32_dpp v28, v28, v28 row_ror:4 row_mask:0xf bank_mask:0xf
	s_nop 1
	v_max_f32_dpp v28, v28, v28 row_ror:2 row_mask:0xf bank_mask:0xf
	v_mov_b32_e32 v32, v0
	s_nop 1
	v_mov_b32_dpp v32, v28 row_ror:1 row_mask:0xf bank_mask:0xf
	v_max3_f32 v83, v78, v28, v32
	v_sub_f32_e32 v29, v29, v83
	v_mul_f32_e32 v29, 0x3fb8aa3b, v29
	v_exp_f32_e32 v62, v29
	v_sub_f32_e32 v29, v33, v83
	v_mul_f32_e32 v29, 0x3fb8aa3b, v29
	v_exp_f32_e32 v60, v29
	v_sub_f32_e32 v29, v37, v83
	v_mul_f32_e32 v29, 0x3fb8aa3b, v29
	v_exp_f32_e32 v58, v29
	v_sub_f32_e32 v29, v41, v83
	v_sub_f32_e32 v28, v78, v83
	v_mul_f32_e32 v29, 0x3fb8aa3b, v29
	v_mul_f32_e32 v28, 0x3fb8aa3b, v28
	v_exp_f32_e32 v56, v29
	v_exp_f32_e32 v80, v28
	v_pk_add_f32 v[28:29], v[62:63], 0 op_sel_hi:[1,0]
	v_pk_add_f32 v[28:29], v[60:61], v[28:29]
	v_pk_add_f32 v[28:29], v[58:59], v[28:29]
	s_nop 0
	v_pk_add_f32 v[28:29], v[56:57], v[28:29]
	s_nop 1
	v_add_f32_dpp v28, v28, v28 row_ror:8 row_mask:0xf bank_mask:0xf
	v_add_f32_dpp v29, v29, v29 row_ror:8 row_mask:0xf bank_mask:0xf
	s_nop 0
	v_add_f32_dpp v28, v28, v28 row_ror:4 row_mask:0xf bank_mask:0xf
	v_add_f32_dpp v29, v29, v29 row_ror:4 row_mask:0xf bank_mask:0xf
	s_nop 0
	v_add_f32_dpp v28, v28, v28 row_ror:2 row_mask:0xf bank_mask:0xf
	v_add_f32_dpp v29, v29, v29 row_ror:2 row_mask:0xf bank_mask:0xf
	v_mov_b32_e32 v33, v0
	v_mov_b32_e32 v32, v0
	s_nop 0
	v_mov_b32_dpp v33, v29 row_ror:1 row_mask:0xf bank_mask:0xf
	v_mov_b32_dpp v32, v28 row_ror:1 row_mask:0xf bank_mask:0xf
	v_pk_add_f32 v[28:29], v[28:29], v[32:33]
	s_nop 0
	v_pk_fma_f32 v[54:55], v[54:55], v[80:81], v[28:29]
	v_max_f32_e32 v28, v42, v42
	v_max_f32_e32 v29, v38, v38
	v_max_f32_e32 v28, v29, v28
	v_max3_f32 v28, v30, v34, v28
	s_nop 1
	v_max_f32_dpp v28, v28, v28 row_ror:8 row_mask:0xf bank_mask:0xf
	s_nop 1
	v_max_f32_dpp v28, v28, v28 row_ror:4 row_mask:0xf bank_mask:0xf
	s_nop 1
	v_max_f32_dpp v28, v28, v28 row_ror:2 row_mask:0xf bank_mask:0xf
	v_mov_b32_e32 v29, v0
	s_nop 1
	v_mov_b32_dpp v29, v28 row_ror:1 row_mask:0xf bank_mask:0xf
	v_max3_f32 v84, v79, v28, v29
	v_sub_f32_e32 v29, v30, v84
	v_sub_f32_e32 v30, v34, v84
	v_mul_f32_e32 v30, 0x3fb8aa3b, v30
	v_exp_f32_e32 v33, v30
	v_sub_f32_e32 v30, v38, v84
	v_mul_f32_e32 v30, 0x3fb8aa3b, v30
	v_sub_f32_e32 v28, v79, v84
	v_exp_f32_e32 v37, v30
	v_sub_f32_e32 v30, v42, v84
	v_mul_f32_e32 v28, 0x3fb8aa3b, v28
	v_mul_f32_e32 v30, 0x3fb8aa3b, v30
	v_exp_f32_e32 v41, v30
	v_exp_f32_e32 v79, v28
	v_max_f32_e32 v28, v43, v43
	v_max_f32_e32 v30, v39, v39
	v_max_f32_e32 v28, v30, v28
	v_max3_f32 v28, v31, v35, v28
	v_mul_f32_e32 v29, 0x3fb8aa3b, v29
	v_exp_f32_e32 v29, v29
	v_max_f32_dpp v28, v28, v28 row_ror:8 row_mask:0xf bank_mask:0xf
	v_mov_b32_e32 v34, v0
	s_nop 0
	v_max_f32_dpp v28, v28, v28 row_ror:4 row_mask:0xf bank_mask:0xf
	s_nop 1
	v_max_f32_dpp v28, v28, v28 row_ror:2 row_mask:0xf bank_mask:0xf
	v_mov_b32_e32 v30, v0
	s_nop 1
	v_mov_b32_dpp v30, v28 row_ror:1 row_mask:0xf bank_mask:0xf
	v_max3_f32 v42, v1, v28, v30
	v_sub_f32_e32 v1, v1, v42
	v_mul_f32_e32 v1, 0x3fb8aa3b, v1
	v_sub_f32_e32 v28, v31, v42
	v_exp_f32_e32 v78, v1
	v_mul_f32_e32 v28, 0x3fb8aa3b, v28
	v_cvt_pk_bf16_f32 v1, v63, v63
	v_exp_f32_e32 v28, v28
	ds_write_b16_d16_hi v74, v1 offset:18432
	v_cvt_pk_bf16_f32 v1, v62, v62
	ds_write_b16_d16_hi v74, v1 offset:18576
	v_cvt_pk_bf16_f32 v1, v29, v29
	ds_write_b16_d16_hi v74, v1 offset:18720
	v_cvt_pk_bf16_f32 v1, v28, v28
	v_sub_f32_e32 v30, v35, v42
	ds_write_b16_d16_hi v74, v1 offset:18864
	v_mul_f32_e32 v30, 0x3fb8aa3b, v30
	v_cvt_pk_bf16_f32 v1, v61, v61
	v_exp_f32_e32 v32, v30
	ds_write_b16_d16_hi v74, v1 offset:18464
	v_cvt_pk_bf16_f32 v1, v60, v60
	ds_write_b16_d16_hi v74, v1 offset:18608
	v_cvt_pk_bf16_f32 v1, v33, v33
	ds_write_b16_d16_hi v74, v1 offset:18752
	v_sub_f32_e32 v30, v39, v42
	v_cvt_pk_bf16_f32 v1, v32, v32
	v_mul_f32_e32 v30, 0x3fb8aa3b, v30
	ds_write_b16_d16_hi v74, v1 offset:18896
	v_exp_f32_e32 v36, v30
	v_sub_f32_e32 v30, v43, v42
	v_cvt_pk_bf16_f32 v1, v59, v59
	v_mul_f32_e32 v30, 0x3fb8aa3b, v30
	ds_write_b16_d16_hi v74, v1 offset:18496
	v_exp_f32_e32 v40, v30
	v_cvt_pk_bf16_f32 v1, v58, v58
	v_pk_add_f32 v[30:31], v[28:29], 0 op_sel_hi:[1,0]
	ds_write_b16_d16_hi v74, v1 offset:18640
	v_pk_add_f32 v[30:31], v[32:33], v[30:31]
	v_cvt_pk_bf16_f32 v1, v37, v37
	v_pk_add_f32 v[30:31], v[36:37], v[30:31]
	ds_write_b16_d16_hi v74, v1 offset:18784
	v_pk_add_f32 v[30:31], v[40:41], v[30:31]
	v_mov_b32_e32 v35, v0
	v_cvt_pk_bf16_f32 v1, v36, v36
	v_mov_b32_dpp v34, v30 row_ror:8 row_mask:0xf bank_mask:0xf
	v_mov_b32_dpp v35, v31 row_ror:8 row_mask:0xf bank_mask:0xf
	ds_write_b16_d16_hi v74, v1 offset:18928
	v_pk_add_f32 v[30:31], v[30:31], v[34:35]
	v_cvt_pk_bf16_f32 v1, v57, v57
	ds_write_b16_d16_hi v74, v1 offset:18528
	v_add_f32_dpp v30, v30, v30 row_ror:4 row_mask:0xf bank_mask:0xf
	v_add_f32_dpp v31, v31, v31 row_ror:4 row_mask:0xf bank_mask:0xf
	v_cvt_pk_bf16_f32 v1, v56, v56
	ds_write_b16_d16_hi v74, v1 offset:18672
	v_add_f32_dpp v30, v30, v30 row_ror:2 row_mask:0xf bank_mask:0xf
	v_add_f32_dpp v31, v31, v31 row_ror:2 row_mask:0xf bank_mask:0xf
	v_cvt_pk_bf16_f32 v1, v41, v41
	ds_write_b16_d16_hi v74, v1 offset:18816
	v_add_f32_dpp v30, v30, v30 row_ror:1 row_mask:0xf bank_mask:0xf
	v_add_f32_dpp v31, v31, v31 row_ror:1 row_mask:0xf bank_mask:0xf
	v_cvt_pk_bf16_f32 v1, v40, v40
	v_pk_fma_f32 v[2:3], v[2:3], v[78:79], v[30:31]
	v_mov_b32_e32 v30, v79
	v_mov_b32_e32 v31, v78
	v_mov_b32_e32 v34, v81
	v_mov_b32_e32 v35, v80
	ds_write_b16_d16_hi v74, v1 offset:18960
	v_pk_mul_f32 v[14:15], v[14:15], v[30:31]
	v_pk_mul_f32 v[12:13], v[12:13], v[34:35]
	v_pk_mul_f32 v[18:19], v[18:19], v[30:31]
	v_pk_mul_f32 v[16:17], v[16:17], v[34:35]
	v_pk_mul_f32 v[22:23], v[22:23], v[30:31]
	v_pk_mul_f32 v[20:21], v[20:21], v[34:35]
	v_pk_mul_f32 v[26:27], v[26:27], v[30:31]
	v_pk_mul_f32 v[24:25], v[24:25], v[34:35]
	ds_read_b128 v[28:31], v75 offset:18432
	ds_read_b128 v[32:35], v75 offset:18496
	ds_read_b128 v[36:39], v77 offset:9216
	s_waitcnt lgkmcnt(0)
	v_mfma_f32_16x16x32_bf16 v[12:15], v[28:31], v[36:39], v[12:15]
	ds_read_b128 v[36:39], v77 offset:9280
	v_mov_b32_e32 v1, v42
	v_mov_b32_e32 v79, v84
	s_waitcnt lgkmcnt(0)
	v_mfma_f32_16x16x32_bf16 v[12:15], v[32:35], v[36:39], v[12:15]
	ds_read_b128 v[36:39], v77 offset:11520
	v_mov_b32_e32 v80, v82
	v_mov_b32_e32 v78, v83
	s_waitcnt lgkmcnt(0)
	v_mfma_f32_16x16x32_bf16 v[16:19], v[28:31], v[36:39], v[16:19]
	ds_read_b128 v[36:39], v77 offset:11584
	s_waitcnt lgkmcnt(0)
	v_mfma_f32_16x16x32_bf16 v[16:19], v[32:35], v[36:39], v[16:19]
	ds_read_b128 v[36:39], v77 offset:13824
	s_waitcnt lgkmcnt(0)
	v_mfma_f32_16x16x32_bf16 v[20:23], v[28:31], v[36:39], v[20:23]
	ds_read_b128 v[36:39], v77 offset:13888
	s_waitcnt lgkmcnt(0)
	v_mfma_f32_16x16x32_bf16 v[20:23], v[32:35], v[36:39], v[20:23]
	ds_read_b128 v[36:39], v77 offset:16128
	s_waitcnt lgkmcnt(0)
	v_mfma_f32_16x16x32_bf16 v[24:27], v[28:31], v[36:39], v[24:27]
	ds_read_b128 v[28:31], v77 offset:16192
	s_waitcnt lgkmcnt(0)
	s_barrier
	v_mfma_f32_16x16x32_bf16 v[24:27], v[32:35], v[28:31], v[24:27]
